# ctx rows split-K partial sums in N1/N2: 16 loads per batch instead of one load per wait
# baseline (speedup 1.0000x reference)
; __device__ __forceinline__ void norm_rows(const float* srcL, const float* srcC, const float* g, const float* mv, int sc_idx, int sh_idx, bf16* out, int nrows, int gw, int NGW, int lane, const float* part, int nsplit, float* wb) {
;     ...
;         if (isc && nsplit > 0) {
;             const f32x4* pp = (const f32x4*)(part + (size_t)(row - ML) * DM) + lane;
; #pragma unroll 4
;             for (int sp = 0; sp < nsplit; ++sp) {
; #pragma unroll
;                 for (int j = 0; j < 8; ++j) v[j] += pp[(size_t)sp * (MC * DM / 4) + 64 * j];
;             }
.LBB0_256:
	s_add_i32 s26, s26, 4
	s_mov_b32 s4, 0xff3fe400
	v_add_co_u32_e32 v70, vcc, s4, v50
	s_nop 1
	v_addc_co_u32_e32 v71, vcc, -1, v51, vcc
	global_load_dwordx4 v[120:123], v[70:71], off
	global_load_dwordx4 v[124:127], v[70:71], off offset:1024
	global_load_dwordx4 v[128:131], v[70:71], off offset:2048
	global_load_dwordx4 v[132:135], v[70:71], off offset:3072
	v_add_co_u32_e32 v70, vcc, 0x1000, v70
	s_nop 1
	v_addc_co_u32_e32 v71, vcc, 0, v71, vcc
	global_load_dwordx4 v[136:139], v[70:71], off
	global_load_dwordx4 v[140:143], v[70:71], off offset:1024
	global_load_dwordx4 v[150:153], v[70:71], off offset:2048
	global_load_dwordx4 v[154:157], v[70:71], off offset:3072
	v_add_co_u32_e32 v70, vcc, 0x3ff000, v70
	s_nop 1
	v_addc_co_u32_e32 v71, vcc, 0, v71, vcc
	global_load_dwordx4 v[158:161], v[70:71], off
	global_load_dwordx4 v[162:165], v[70:71], off offset:1024
	global_load_dwordx4 v[174:177], v[70:71], off offset:2048
	global_load_dwordx4 v[178:181], v[70:71], off offset:3072
	v_add_co_u32_e32 v70, vcc, 0x1000, v70
	s_nop 1
	v_addc_co_u32_e32 v71, vcc, 0, v71, vcc
	global_load_dwordx4 v[182:185], v[70:71], off
	global_load_dwordx4 v[186:189], v[70:71], off offset:1024
	global_load_dwordx4 v[190:193], v[70:71], off offset:2048
	global_load_dwordx4 v[194:197], v[70:71], off offset:3072
	v_add_co_u32_e32 v70, vcc, 0x3ff000, v70
	s_nop 1
	v_addc_co_u32_e32 v71, vcc, 0, v71, vcc
	s_waitcnt vmcnt(0)
	v_pk_add_f32 v[28:29], v[28:29], v[120:121]
	v_pk_add_f32 v[30:31], v[30:31], v[122:123]
	v_pk_add_f32 v[16:17], v[16:17], v[124:125]
	v_pk_add_f32 v[18:19], v[18:19], v[126:127]
	v_pk_add_f32 v[8:9], v[8:9], v[128:129]
	v_pk_add_f32 v[10:11], v[10:11], v[130:131]
	v_pk_add_f32 v[0:1], v[0:1], v[132:133]
	v_pk_add_f32 v[2:3], v[2:3], v[134:135]
	v_pk_add_f32 v[24:25], v[24:25], v[136:137]
	v_pk_add_f32 v[26:27], v[26:27], v[138:139]
	v_pk_add_f32 v[20:21], v[20:21], v[140:141]
	v_pk_add_f32 v[22:23], v[22:23], v[142:143]
	v_pk_add_f32 v[12:13], v[12:13], v[150:151]
	v_pk_add_f32 v[14:15], v[14:15], v[152:153]
	v_pk_add_f32 v[4:5], v[4:5], v[154:155]
	v_pk_add_f32 v[6:7], v[6:7], v[156:157]
	v_pk_add_f32 v[28:29], v[28:29], v[158:159]
	v_pk_add_f32 v[30:31], v[30:31], v[160:161]
	v_pk_add_f32 v[16:17], v[16:17], v[162:163]
	v_pk_add_f32 v[18:19], v[18:19], v[164:165]
	v_pk_add_f32 v[8:9], v[8:9], v[174:175]
	v_pk_add_f32 v[10:11], v[10:11], v[176:177]
	v_pk_add_f32 v[0:1], v[0:1], v[178:179]
	v_pk_add_f32 v[2:3], v[2:3], v[180:181]
	v_pk_add_f32 v[24:25], v[24:25], v[182:183]
	v_pk_add_f32 v[26:27], v[26:27], v[184:185]
	v_pk_add_f32 v[20:21], v[20:21], v[186:187]
	v_pk_add_f32 v[22:23], v[22:23], v[188:189]
	v_pk_add_f32 v[12:13], v[12:13], v[190:191]
	v_pk_add_f32 v[14:15], v[14:15], v[192:193]
	v_pk_add_f32 v[4:5], v[4:5], v[194:195]
	v_pk_add_f32 v[6:7], v[6:7], v[196:197]
	global_load_dwordx4 v[120:123], v[70:71], off
	global_load_dwordx4 v[124:127], v[70:71], off offset:1024
	global_load_dwordx4 v[128:131], v[70:71], off offset:2048
	global_load_dwordx4 v[132:135], v[70:71], off offset:3072
	v_add_co_u32_e32 v70, vcc, 0x1000, v70
	s_nop 1
	v_addc_co_u32_e32 v71, vcc, 0, v71, vcc
	global_load_dwordx4 v[136:139], v[70:71], off
	global_load_dwordx4 v[140:143], v[70:71], off offset:1024
	global_load_dwordx4 v[150:153], v[70:71], off offset:2048
	global_load_dwordx4 v[154:157], v[70:71], off offset:3072
	v_add_co_u32_e32 v70, vcc, 0x3ff000, v70
	s_nop 1
	v_addc_co_u32_e32 v71, vcc, 0, v71, vcc
	global_load_dwordx4 v[158:161], v[70:71], off
	global_load_dwordx4 v[162:165], v[70:71], off offset:1024
	global_load_dwordx4 v[174:177], v[70:71], off offset:2048
	global_load_dwordx4 v[178:181], v[70:71], off offset:3072
	v_add_co_u32_e32 v70, vcc, 0x1000, v70
	s_nop 1
	v_addc_co_u32_e32 v71, vcc, 0, v71, vcc
	global_load_dwordx4 v[182:185], v[70:71], off
	global_load_dwordx4 v[186:189], v[70:71], off offset:1024
	global_load_dwordx4 v[190:193], v[70:71], off offset:2048
	global_load_dwordx4 v[194:197], v[70:71], off offset:3072
	s_waitcnt vmcnt(0)
	v_pk_add_f32 v[28:29], v[28:29], v[120:121]
	v_pk_add_f32 v[30:31], v[30:31], v[122:123]
	v_pk_add_f32 v[16:17], v[16:17], v[124:125]
	v_pk_add_f32 v[18:19], v[18:19], v[126:127]
	v_pk_add_f32 v[8:9], v[8:9], v[128:129]
	v_pk_add_f32 v[10:11], v[10:11], v[130:131]
	v_pk_add_f32 v[0:1], v[0:1], v[132:133]
	v_pk_add_f32 v[2:3], v[2:3], v[134:135]
	v_pk_add_f32 v[24:25], v[24:25], v[136:137]
	v_pk_add_f32 v[26:27], v[26:27], v[138:139]
	v_pk_add_f32 v[20:21], v[20:21], v[140:141]
	v_pk_add_f32 v[22:23], v[22:23], v[142:143]
	v_pk_add_f32 v[12:13], v[12:13], v[150:151]
	v_pk_add_f32 v[14:15], v[14:15], v[152:153]
	v_pk_add_f32 v[4:5], v[4:5], v[154:155]
	v_pk_add_f32 v[6:7], v[6:7], v[156:157]
	v_pk_add_f32 v[28:29], v[28:29], v[158:159]
	v_pk_add_f32 v[30:31], v[30:31], v[160:161]
	v_pk_add_f32 v[16:17], v[16:17], v[162:163]
	v_pk_add_f32 v[18:19], v[18:19], v[164:165]
	v_pk_add_f32 v[8:9], v[8:9], v[174:175]
	v_pk_add_f32 v[10:11], v[10:11], v[176:177]
	v_pk_add_f32 v[0:1], v[0:1], v[178:179]
	v_pk_add_f32 v[2:3], v[2:3], v[180:181]
	v_pk_add_f32 v[24:25], v[24:25], v[182:183]
	v_pk_add_f32 v[26:27], v[26:27], v[184:185]
	v_pk_add_f32 v[20:21], v[20:21], v[186:187]
	v_pk_add_f32 v[22:23], v[22:23], v[188:189]
	v_pk_add_f32 v[12:13], v[12:13], v[190:191]
	v_pk_add_f32 v[14:15], v[14:15], v[192:193]
	v_pk_add_f32 v[4:5], v[4:5], v[194:195]
	v_pk_add_f32 v[6:7], v[6:7], v[196:197]
	v_lshl_add_u64 v[50:51], v[50:51], 0, s[28:29]
	s_cmp_lg_u32 s31, s26
	s_cbranch_scc1 .LBB0_256
	s_mov_b32 s26, s31

; __device__ __forceinline__ void norm_rows(const float* srcL, const float* srcC, const float* g, const float* mv, int sc_idx, int sh_idx, bf16* out, int nrows, int gw, int NGW, int lane, const float* part, int nsplit, float* wb) {
;     ...
;         const f32x4* src = (const f32x4*)(isc ? srcC + (size_t)(row - ML) * DM : srcL + (size_t)row * DM) + lane;
;         const float* mvv = mv + (isc ? 2 : (row >> 13)) * ADA;
;         f32x4 v[8]; float s = 0.f;
; #pragma unroll
;         for (int j = 0; j < 8; ++j) v[j] = src[64 * j];
;         if (isc && nsplit > 0) {
;             const f32x4* pp = (const f32x4*)(part + (size_t)(row - ML) * DM) + lane;
; #pragma unroll 4
;             for (int sp = 0; sp < nsplit; ++sp) {
; #pragma unroll
;                 for (int j = 0; j < 8; ++j) v[j] += pp[(size_t)sp * (MC * DM / 4) + 64 * j];
;             }
;             if (wb) { f32x4* w4 = (f32x4*)(wb + (size_t)(row - ML) * DM) + lane;
; #pragma unroll
;                 for (int j = 0; j < 8; ++j) w4[64 * j] = v[j]; }
.LBB0_952:
	s_add_i32 s24, s0, 0xffffc000
	s_cmpk_gt_i32 s0, 0x3fff
	s_cselect_b64 s[4:5], -1, 0
	s_and_b64 s[8:9], s[4:5], exec
	s_cselect_b32 s9, 0, s1
	s_cselect_b32 s8, s24, s0
	s_cselect_b32 s10, s12, s41
	s_cselect_b32 s11, s13, s40
	s_lshl_b64 s[8:9], s[8:9], 13
	s_add_u32 s8, s11, s8
	s_addc_u32 s9, s10, s9
	v_lshl_add_u64 v[0:1], s[8:9], 0, v[34:35]
	v_add_co_u32_e32 v28, vcc, 0x1000, v0
	global_load_dwordx4 v[24:27], v34, s[8:9]
	global_load_dwordx4 v[20:23], v34, s[8:9] offset:1024
	global_load_dwordx4 v[16:19], v34, s[8:9] offset:2048
	global_load_dwordx4 v[12:15], v34, s[8:9] offset:3072
	v_addc_co_u32_e32 v29, vcc, 0, v1, vcc
	global_load_dwordx4 v[8:11], v[28:29], off
	global_load_dwordx4 v[4:7], v[28:29], off offset:1024
	global_load_dwordx4 v[0:3], v[28:29], off offset:2048
	s_nop 0
	global_load_dwordx4 v[28:31], v[28:29], off offset:3072
	s_and_b64 s[4:5], s[74:75], s[4:5]
	s_andn2_b64 vcc, exec, s[4:5]
	s_cbranch_vccnz .LBB0_951
	s_lshl_b64 s[8:9], s[24:25], 13
	v_lshl_add_u64 v[54:55], v[32:33], 0, s[8:9]
	v_mov_b64_e32 v[70:71], v[54:55]
	global_load_dwordx4 v[100:103], v[70:71], off
	global_load_dwordx4 v[104:107], v[70:71], off offset:1024
	global_load_dwordx4 v[108:111], v[70:71], off offset:2048
	global_load_dwordx4 v[112:115], v[70:71], off offset:3072
	v_add_co_u32_e32 v70, vcc, 0x1000, v70
	s_nop 1
	v_addc_co_u32_e32 v71, vcc, 0, v71, vcc
	global_load_dwordx4 v[116:119], v[70:71], off
	global_load_dwordx4 v[120:123], v[70:71], off offset:1024
	global_load_dwordx4 v[124:127], v[70:71], off offset:2048
	global_load_dwordx4 v[128:131], v[70:71], off offset:3072
	v_add_co_u32_e32 v70, vcc, 0x3ff000, v70
	s_nop 1
	v_addc_co_u32_e32 v71, vcc, 0, v71, vcc
	global_load_dwordx4 v[132:135], v[70:71], off
	global_load_dwordx4 v[136:139], v[70:71], off offset:1024
	global_load_dwordx4 v[140:143], v[70:71], off offset:2048
	global_load_dwordx4 v[150:153], v[70:71], off offset:3072
	v_add_co_u32_e32 v70, vcc, 0x1000, v70
	s_nop 1
	v_addc_co_u32_e32 v71, vcc, 0, v71, vcc
	global_load_dwordx4 v[154:157], v[70:71], off
	global_load_dwordx4 v[158:161], v[70:71], off offset:1024
	global_load_dwordx4 v[162:165], v[70:71], off offset:2048
	global_load_dwordx4 v[174:177], v[70:71], off offset:3072
	v_add_co_u32_e32 v70, vcc, 0x3ff000, v70
	s_nop 1
	v_addc_co_u32_e32 v71, vcc, 0, v71, vcc
	s_waitcnt vmcnt(0)
	v_pk_add_f32 v[24:25], v[24:25], v[100:101]
	v_pk_add_f32 v[26:27], v[26:27], v[102:103]
	v_pk_add_f32 v[20:21], v[20:21], v[104:105]
	v_pk_add_f32 v[22:23], v[22:23], v[106:107]
	v_pk_add_f32 v[16:17], v[16:17], v[108:109]
	v_pk_add_f32 v[18:19], v[18:19], v[110:111]
	v_pk_add_f32 v[12:13], v[12:13], v[112:113]
	v_pk_add_f32 v[14:15], v[14:15], v[114:115]
	v_pk_add_f32 v[8:9], v[8:9], v[116:117]
	v_pk_add_f32 v[10:11], v[10:11], v[118:119]
	v_pk_add_f32 v[4:5], v[4:5], v[120:121]
	v_pk_add_f32 v[6:7], v[6:7], v[122:123]
	v_pk_add_f32 v[0:1], v[0:1], v[124:125]
	v_pk_add_f32 v[2:3], v[2:3], v[126:127]
	v_pk_add_f32 v[28:29], v[28:29], v[128:129]
	v_pk_add_f32 v[30:31], v[30:31], v[130:131]
	v_pk_add_f32 v[24:25], v[24:25], v[132:133]
	v_pk_add_f32 v[26:27], v[26:27], v[134:135]
	v_pk_add_f32 v[20:21], v[20:21], v[136:137]
	v_pk_add_f32 v[22:23], v[22:23], v[138:139]
	v_pk_add_f32 v[16:17], v[16:17], v[140:141]
	v_pk_add_f32 v[18:19], v[18:19], v[142:143]
	v_pk_add_f32 v[12:13], v[12:13], v[150:151]
	v_pk_add_f32 v[14:15], v[14:15], v[152:153]
	v_pk_add_f32 v[8:9], v[8:9], v[154:155]
	v_pk_add_f32 v[10:11], v[10:11], v[156:157]
	v_pk_add_f32 v[4:5], v[4:5], v[158:159]
	v_pk_add_f32 v[6:7], v[6:7], v[160:161]
	v_pk_add_f32 v[0:1], v[0:1], v[162:163]
	v_pk_add_f32 v[2:3], v[2:3], v[164:165]
	v_pk_add_f32 v[28:29], v[28:29], v[174:175]
	v_pk_add_f32 v[30:31], v[30:31], v[176:177]
	global_load_dwordx4 v[100:103], v[70:71], off
	global_load_dwordx4 v[104:107], v[70:71], off offset:1024
	global_load_dwordx4 v[108:111], v[70:71], off offset:2048
	global_load_dwordx4 v[112:115], v[70:71], off offset:3072
	v_add_co_u32_e32 v70, vcc, 0x1000, v70
	s_nop 1
	v_addc_co_u32_e32 v71, vcc, 0, v71, vcc
	global_load_dwordx4 v[116:119], v[70:71], off
	global_load_dwordx4 v[120:123], v[70:71], off offset:1024
	global_load_dwordx4 v[124:127], v[70:71], off offset:2048
	global_load_dwordx4 v[128:131], v[70:71], off offset:3072
	v_add_co_u32_e32 v70, vcc, 0x3ff000, v70
	s_nop 1
	v_addc_co_u32_e32 v71, vcc, 0, v71, vcc
	global_load_dwordx4 v[132:135], v[70:71], off
	global_load_dwordx4 v[136:139], v[70:71], off offset:1024
	global_load_dwordx4 v[140:143], v[70:71], off offset:2048
	global_load_dwordx4 v[150:153], v[70:71], off offset:3072
	v_add_co_u32_e32 v70, vcc, 0x1000, v70
	s_nop 1
	v_addc_co_u32_e32 v71, vcc, 0, v71, vcc
	global_load_dwordx4 v[154:157], v[70:71], off
	global_load_dwordx4 v[158:161], v[70:71], off offset:1024
	global_load_dwordx4 v[162:165], v[70:71], off offset:2048
	global_load_dwordx4 v[174:177], v[70:71], off offset:3072
	s_waitcnt vmcnt(0)
	v_pk_add_f32 v[24:25], v[24:25], v[100:101]
	v_pk_add_f32 v[26:27], v[26:27], v[102:103]
	v_pk_add_f32 v[20:21], v[20:21], v[104:105]
	v_pk_add_f32 v[22:23], v[22:23], v[106:107]
	v_pk_add_f32 v[16:17], v[16:17], v[108:109]
	v_pk_add_f32 v[18:19], v[18:19], v[110:111]
	v_pk_add_f32 v[12:13], v[12:13], v[112:113]
	v_pk_add_f32 v[14:15], v[14:15], v[114:115]
	v_pk_add_f32 v[8:9], v[8:9], v[116:117]
	v_pk_add_f32 v[10:11], v[10:11], v[118:119]
	v_pk_add_f32 v[4:5], v[4:5], v[120:121]
	v_pk_add_f32 v[6:7], v[6:7], v[122:123]
	v_pk_add_f32 v[0:1], v[0:1], v[124:125]
	v_pk_add_f32 v[2:3], v[2:3], v[126:127]
	v_pk_add_f32 v[28:29], v[28:29], v[128:129]
	v_pk_add_f32 v[30:31], v[30:31], v[130:131]
	v_pk_add_f32 v[24:25], v[24:25], v[132:133]
	v_pk_add_f32 v[26:27], v[26:27], v[134:135]
	v_pk_add_f32 v[20:21], v[20:21], v[136:137]
	v_pk_add_f32 v[22:23], v[22:23], v[138:139]
	v_pk_add_f32 v[16:17], v[16:17], v[140:141]
	v_pk_add_f32 v[18:19], v[18:19], v[142:143]
	v_pk_add_f32 v[12:13], v[12:13], v[150:151]
	v_pk_add_f32 v[14:15], v[14:15], v[152:153]
	v_pk_add_f32 v[8:9], v[8:9], v[154:155]
	v_pk_add_f32 v[10:11], v[10:11], v[156:157]
	v_pk_add_f32 v[4:5], v[4:5], v[158:159]
	v_pk_add_f32 v[6:7], v[6:7], v[160:161]
	v_pk_add_f32 v[0:1], v[0:1], v[162:163]
	v_pk_add_f32 v[2:3], v[2:3], v[164:165]
	v_pk_add_f32 v[28:29], v[28:29], v[174:175]
	v_pk_add_f32 v[30:31], v[30:31], v[176:177]
	v_lshl_add_u64 v[50:51], v[36:37], 0, s[8:9]
	global_store_dwordx4 v[50:51], v[24:27], off
	global_store_dwordx4 v[50:51], v[20:23], off offset:1024
	global_store_dwordx4 v[50:51], v[16:19], off offset:2048
	global_store_dwordx4 v[50:51], v[12:15], off offset:3072
	v_add_co_u32_e32 v50, vcc, s16, v50
	s_nop 1
	v_addc_co_u32_e32 v51, vcc, 0, v51, vcc
	global_store_dwordx4 v[50:51], v[8:11], off
	global_store_dwordx4 v[50:51], v[4:7], off offset:1024
	global_store_dwordx4 v[50:51], v[0:3], off offset:2048
	global_store_dwordx4 v[50:51], v[28:31], off offset:3072
	s_branch .LBB0_951
